# LN3 row loop: removed the vmcnt(0) that serialized the first row's loads before the other three rows' loads (all 8 loads of an iteration now in flight together)
# speedup vs baseline: 1.0065x; 1.0065x over previous
; __device__ __forceinline__ float wave_sum(float v) { return rdlane(dpp_sum63(v), 63); }
; __device__ __forceinline__ void row_ln(f32x4 (&v)[4], const float* g, const float* b, int lane) {
;     float s = 0.f;
; #pragma unroll
;     for (int j = 0; j < 4; ++j) s += (v[j][0] + v[j][1]) + (v[j][2] + v[j][3]);
;     const float mean = wave_sum(s) * (1.f / D); float s2 = 0.f;
; #pragma unroll
;     for (int j = 0; j < 4; ++j) { v[j] = v[j] - mean; s2 += (v[j][0] * v[j][0] + v[j][1] * v[j][1]) + (v[j][2] * v[j][2] + v[j][3] * v[j][3]); }
;     const float rstd = 1.0f / sqrtf(wave_sum(s2) * (1.f / D) + LN_EPS);
; #pragma unroll
;     for (int j = 0; j < 4; ++j) { const f32x4 gg = *(const f32x4*)(g + RCOL(lane, j)), bb = *(const f32x4*)(b + RCOL(lane, j)); v[j] = v[j] * rstd * gg + bb; }
; }
; __global__ void __launch_bounds__(NT, 2) fwd(const Args args) {
;     ...
;             for (int m = m0; m < m1; m += 4) { u32x4 r[4][2];
; #pragma unroll
;                 for (int q = 0; q < 4; ++q) { const int mm = (m + q < m1) ? m + q : m1 - 1; row_raw(X + (size_t)mm * D, F.lane, r[q]); }
; #pragma unroll
;                 for (int q = 0; q < 4; ++q) if (m + q < m1) { f32x4 v[4]; row_unpack(r[q], v); row_ln(v, g, bb, F.lane);
.LBB0_1697:
	s_add_i32 s28, s6, 1
	s_min_i32 s10, s28, s12
	s_ashr_i32 s11, s10, 31
	s_lshl_b64 s[10:11], s[10:11], 11
	s_add_i32 s27, s6, 2
	v_lshl_add_u64 v[4:5], v[52:53], 0, s[10:11]
	s_min_i32 s10, s27, s12
	s_ashr_i32 s11, s10, 31
	s_lshl_b64 s[10:11], s[10:11], 11
	s_add_i32 s7, s6, 3
	global_load_dwordx4 v[20:23], v[4:5], off
	global_load_dwordx4 v[24:27], v[4:5], off offset:1024
	v_lshl_add_u64 v[4:5], v[52:53], 0, s[10:11]
	s_min_i32 s10, s7, s12
	s_ashr_i32 s11, s10, 31
	s_lshl_b64 s[10:11], s[10:11], 11
	v_lshl_add_u64 v[8:9], v[52:53], 0, s[10:11]
	s_min_i32 s10, s6, s12
	s_ashr_i32 s11, s10, 31
	s_lshl_b64 s[10:11], s[10:11], 11
	s_nop 0
	v_lshl_add_u64 v[32:33], v[52:53], 0, s[10:11]
	global_load_dwordx4 v[12:15], v[4:5], off
	global_load_dwordx4 v[16:19], v[4:5], off offset:1024
	s_nop 0
	global_load_dwordx4 v[4:7], v[8:9], off
	s_nop 0
	global_load_dwordx4 v[8:11], v[8:9], off offset:1024
	s_nop 0
	global_load_dwordx4 v[28:31], v[32:33], off offset:1024
	s_nop 0
	global_load_dwordx4 v[32:35], v[32:33], off
	s_waitcnt vmcnt(1)
	v_lshlrev_b32_e32 v78, 16, v30
	v_and_b32_e32 v82, 0xffff0000, v30
	v_lshlrev_b32_e32 v76, 16, v31
	v_and_b32_e32 v80, 0xffff0000, v31
	s_waitcnt vmcnt(0)
	v_lshlrev_b32_e32 v31, 16, v33
	v_lshlrev_b32_e32 v30, 16, v32
	v_and_b32_e32 v33, 0xffff0000, v33
	v_and_b32_e32 v32, 0xffff0000, v32
	v_lshlrev_b32_e32 v86, 16, v28
	v_and_b32_e32 v87, 0xffff0000, v28
	v_lshlrev_b32_e32 v84, 16, v29
	v_and_b32_e32 v85, 0xffff0000, v29
	v_pk_add_f32 v[28:29], v[30:31], v[32:33]
	v_and_b32_e32 v37, 0xffff0000, v35
	v_add_f32_e32 v28, v28, v29
	v_add_f32_e32 v81, 0, v28
	v_lshlrev_b32_e32 v29, 16, v35
	v_lshlrev_b32_e32 v28, 16, v34
	v_and_b32_e32 v36, 0xffff0000, v34
	v_pk_add_f32 v[34:35], v[28:29], v[36:37]
	v_add_f32_e32 v79, v86, v87
	v_pk_add_f32 v[34:35], v[34:35], v[34:35] op_sel_hi:[0,1]
	v_add_f32_e32 v83, v84, v85
	v_mov_b32_e32 v77, v35
	v_pk_add_f32 v[38:39], v[78:79], v[82:83]
	v_pk_add_f32 v[34:35], v[76:77], v[80:81]
	s_nop 0
	v_pk_add_f32 v[34:35], v[38:39], v[34:35]
	s_nop 0
	v_add_f32_e32 v34, v34, v35
	v_mov_b32_e32 v35, v2
	s_nop 0
	v_add_f32_dpp v34, v34, v34 quad_perm:[1,0,3,2] row_mask:0xf bank_mask:0xf bound_ctrl:1
	s_nop 1
	v_add_f32_dpp v34, v34, v34 quad_perm:[2,3,0,1] row_mask:0xf bank_mask:0xf bound_ctrl:1
	s_nop 1
	v_add_f32_dpp v34, v34, v34 row_half_mirror row_mask:0xf bank_mask:0xf bound_ctrl:1
	s_nop 1
	v_add_f32_dpp v34, v34, v34 row_mirror row_mask:0xf bank_mask:0xf bound_ctrl:1
	s_nop 1
	v_mov_b32_dpp v35, v34 row_bcast:15 row_mask:0xa bank_mask:0xf
	v_add_f32_e32 v34, v34, v35
	v_mov_b32_e32 v35, v2
	s_nop 1
	v_mov_b32_dpp v35, v34 row_bcast:31 row_mask:0xc bank_mask:0xf
	v_add_f32_e32 v34, v34, v35
	s_nop 0
	v_readlane_b32 s10, v34, 63
	s_nop 1
	v_fmac_f32_e32 v33, s10, v236
	v_fmac_f32_e32 v32, s10, v236
	v_fmac_f32_e32 v31, s10, v236
	v_fmac_f32_e32 v30, s10, v236
	v_mul_f32_e32 v34, v32, v32
	v_mul_f32_e32 v35, v33, v33
	v_fmac_f32_e32 v34, v30, v30
	v_fmac_f32_e32 v35, v31, v31
	v_fmac_f32_e32 v37, s10, v236
	v_fmac_f32_e32 v36, s10, v236
	v_add_f32_e32 v34, v34, v35
	v_fmac_f32_e32 v29, s10, v236
	v_fmac_f32_e32 v28, s10, v236
	v_mul_f32_e32 v35, v36, v36
	v_mul_f32_e32 v38, v37, v37
	v_fmac_f32_e32 v35, v28, v28
	v_fmac_f32_e32 v38, v29, v29
	v_add_f32_e32 v35, v35, v38
	v_fmac_f32_e32 v85, s10, v236
	v_fmac_f32_e32 v87, s10, v236
	v_add_f32_e32 v34, v34, v35
	v_fmac_f32_e32 v84, s10, v236
	v_fmac_f32_e32 v86, s10, v236
	v_mul_f32_e32 v35, v87, v87
	v_mul_f32_e32 v38, v85, v85
	v_fmac_f32_e32 v35, v86, v86
	v_fmac_f32_e32 v38, v84, v84
	v_add_f32_e32 v35, v35, v38
	v_fmac_f32_e32 v80, s10, v236
	v_fmac_f32_e32 v82, s10, v236
	v_add_f32_e32 v34, v35, v34
	v_fmac_f32_e32 v76, s10, v236
	v_fmac_f32_e32 v78, s10, v236
	v_mul_f32_e32 v35, v82, v82
	v_mul_f32_e32 v38, v80, v80
	v_fmac_f32_e32 v35, v78, v78
	v_fmac_f32_e32 v38, v76, v76
	v_add_f32_e32 v35, v35, v38
	v_add_f32_e32 v34, v35, v34
	v_mov_b32_e32 v35, v2
	v_mov_b32_e32 v79, v82
	v_add_f32_dpp v34, v34, v34 quad_perm:[1,0,3,2] row_mask:0xf bank_mask:0xf bound_ctrl:1
	v_mov_b32_e32 v77, v80
	s_nop 0
	v_add_f32_dpp v34, v34, v34 quad_perm:[2,3,0,1] row_mask:0xf bank_mask:0xf bound_ctrl:1
	s_nop 1
	v_add_f32_dpp v34, v34, v34 row_half_mirror row_mask:0xf bank_mask:0xf bound_ctrl:1
	s_nop 1
	v_add_f32_dpp v34, v34, v34 row_mirror row_mask:0xf bank_mask:0xf bound_ctrl:1
	s_nop 1
	v_mov_b32_dpp v35, v34 row_bcast:15 row_mask:0xa bank_mask:0xf
	v_add_f32_e32 v34, v34, v35
	v_mov_b32_e32 v35, v2
	s_nop 1
	v_mov_b32_dpp v35, v34 row_bcast:31 row_mask:0xc bank_mask:0xf
	v_add_f32_e32 v34, v34, v35
	s_nop 0
	v_readlane_b32 s10, v34, 63
	s_nop 1
	v_fma_f32 v34, s10, v237, v252
	v_cmp_gt_f32_e32 vcc, s31, v34
	v_mul_f32_e32 v35, 0x4f800000, v34
	s_nop 0
	v_cndmask_b32_e32 v34, v34, v35, vcc
	v_sqrt_f32_e32 v35, v34
	s_nop 0
	v_add_u32_e32 v38, -1, v35
	v_fma_f32 v39, -v38, v35, v34
	v_cmp_ge_f32_e64 s[54:55], 0, v39
	v_add_u32_e32 v39, 1, v35
	s_nop 0
	v_cndmask_b32_e64 v38, v35, v38, s[54:55]
	v_fma_f32 v35, -v39, v35, v34
	v_cmp_lt_f32_e64 s[54:55], 0, v35
	s_nop 1
	v_cndmask_b32_e64 v35, v38, v39, s[54:55]
	v_mul_f32_e32 v38, 0x37800000, v35
	v_cndmask_b32_e32 v35, v35, v38, vcc
	v_cmp_class_f32_e32 vcc, v34, v234
	s_nop 1
	v_cndmask_b32_e32 v34, v35, v34, vcc
	v_div_scale_f32 v35, s[10:11], v34, v34, 1.0
	v_rcp_f32_e32 v38, v35
	s_mov_b64 s[10:11], -1
	v_fma_f32 v39, -v35, v38, 1.0
	v_fmac_f32_e32 v38, v39, v38
	v_div_scale_f32 v39, vcc, 1.0, v34, 1.0
	v_mul_f32_e32 v40, v39, v38
	v_fma_f32 v41, -v35, v40, v39
	v_fmac_f32_e32 v40, v41, v38
	v_fma_f32 v35, -v35, v40, v39
	v_div_fmas_f32 v35, v35, v38, v40
	global_load_dwordx4 v[38:41], v[56:57], off offset:16
	global_load_dwordx4 v[42:45], v[56:57], off
	global_load_dwordx4 v[46:49], v[58:59], off offset:16
	global_load_dwordx4 v[90:93], v[58:59], off
	v_div_fixup_f32 v88, v35, v34, 1.0
	v_mov_b32_e32 v35, v32
	v_mov_b32_e32 v32, v31
	v_mov_b32_e32 v34, v30
	v_pk_mul_f32 v[30:31], v[32:33], v[88:89] op_sel_hi:[1,0]
	v_pk_mul_f32 v[50:51], v[34:35], v[88:89] op_sel_hi:[1,0]
	v_pk_mul_f32 v[86:87], v[86:87], v[88:89] op_sel_hi:[1,0]
	v_pk_mul_f32 v[84:85], v[84:85], v[88:89] op_sel_hi:[1,0]
	s_andn2_b64 vcc, exec, s[4:5]
	s_waitcnt vmcnt(0)
; __device__ __forceinline__ void row_ln(f32x4 (&v)[4], const float* g, const float* b, int lane) {
;     ...
;     for (int j = 0; j < 4; ++j) { const f32x4 gg = *(const f32x4*)(g + RCOL(lane, j)), bb = *(const f32x4*)(b + RCOL(lane, j)); v[j] = v[j] * rstd * gg + bb; }
; __global__ void __launch_bounds__(NT, 2) fwd(const Args args) {
;     ...
;                     else {
; #pragma unroll
;                         for (int j = 0; j < 4; ++j) *(f32x4*)(F.out + O_Y + (size_t)(m + q) * D + RCOL(F.lane, j)) = v[j]; } } }
	v_pk_fma_f32 v[34:35], v[44:45], v[30:31], v[92:93]
	v_mov_b32_e32 v30, v28
	v_mov_b32_e32 v31, v36
	v_mov_b32_e32 v36, v29
	v_pk_fma_f32 v[32:33], v[42:43], v[50:51], v[90:91]
	v_pk_mul_f32 v[42:43], v[30:31], v[88:89] op_sel_hi:[1,0]
	v_pk_mul_f32 v[28:29], v[36:37], v[88:89] op_sel_hi:[1,0]
	s_nop 0
	v_pk_fma_f32 v[30:31], v[40:41], v[28:29], v[48:49]
	v_pk_fma_f32 v[28:29], v[38:39], v[42:43], v[46:47]
	global_load_dwordx4 v[36:39], v[56:57], off offset:2064
	global_load_dwordx4 v[44:47], v[56:57], off offset:2048
	global_load_dwordx4 v[40:43], v[58:59], off offset:2064
	global_load_dwordx4 v[48:51], v[58:59], off offset:2048
	s_waitcnt vmcnt(0)
	v_pk_fma_f32 v[44:45], v[44:45], v[86:87], v[48:49]
	v_pk_mul_f32 v[48:49], v[78:79], v[88:89] op_sel_hi:[1,0]
	v_pk_fma_f32 v[46:47], v[46:47], v[84:85], v[50:51]
	v_pk_mul_f32 v[50:51], v[76:77], v[88:89] op_sel_hi:[1,0]
	v_pk_fma_f32 v[36:37], v[36:37], v[48:49], v[40:41]
	v_cndmask_b32_e64 v40, 0, 1, s[4:5]
	v_pk_fma_f32 v[38:39], v[38:39], v[50:51], v[42:43]
	v_cmp_ne_u32_e64 s[54:55], 1, v40
	s_cbranch_vccnz .LBB0_1700
	v_lshl_add_u64 v[40:41], s[14:15], 0, v[54:55]
	global_store_dwordx4 v[40:41], v[32:35], off
	global_store_dwordx4 v[40:41], v[28:31], off offset:16
	global_store_dwordx4 v[40:41], v[44:47], off offset:2048
	global_store_dwordx4 v[40:41], v[36:39], off offset:2064
	s_cbranch_execz .LBB0_1701
